# v43
# baseline (speedup 1.0000x reference)
.LBB0_479:
	s_or_b64 exec, exec, s[12:13]
	s_bitcmp1_b32 s31, 0
	v_and_b32_e32 v32, 64, v104
	s_cselect_b32 s12, 0x5180, 0
	v_add_u32_e32 v43, 64, v32
	v_xor_b32_e32 v32, 32, v104
	v_add_u32_e32 v37, s12, v72
	v_cmp_lt_i32_e64 s[12:13], v32, v43
	s_waitcnt vmcnt(47)
	v_lshlrev_b32_e32 v33, 16, v106
	s_waitcnt vmcnt(43)
	v_lshlrev_b32_e32 v34, 16, v112
	v_cndmask_b32_e64 v32, v104, v32, s[12:13]
	v_lshlrev_b32_e32 v38, 2, v32
	s_waitcnt vmcnt(40)
	v_lshlrev_b32_e32 v32, 16, v113
	v_sub_f32_e32 v32, 1.0, v32
	v_mul_f32_e32 v45, v32, v44
	v_rcp_f32_e32 v32, v45
	v_mul_f32_e32 v50, v45, v33
	v_add_f32_e32 v33, -1.0, v34
	v_lshlrev_b32_e32 v46, 16, v111
	v_lshlrev_b32_e32 v35, 16, v108
	s_waitcnt vmcnt(0)
	v_fma_f32 v47, v105, v33, 1.0
	v_pk_mul_f32 v[34:35], v[46:47], v[34:35]
	v_xor_b32_e32 v39, 16, v104
	v_pk_mul_f32 v[158:159], v[34:35], v[32:33] op_sel_hi:[1,0]
	v_cmp_lt_i32_e64 s[12:13], v39, v43
	v_pk_mul_f32 v[32:33], v[50:51], v[158:159] op_sel_hi:[0,1]
	ds_bpermute_b32 v32, v38, v32
	ds_bpermute_b32 v33, v38, v33
	v_cndmask_b32_e64 v34, v104, v39, s[12:13]
	v_lshlrev_b32_e32 v39, 2, v34
	v_xor_b32_e32 v40, 8, v104
	v_cmp_lt_i32_e64 s[12:13], v40, v43
	s_waitcnt lgkmcnt(0)
	v_pk_fma_f32 v[32:33], v[50:51], v[158:159], v[32:33] op_sel_hi:[0,1,1]
	ds_bpermute_b32 v34, v39, v32
	ds_bpermute_b32 v35, v39, v33
	v_cndmask_b32_e64 v40, v104, v40, s[12:13]
	v_lshlrev_b32_e32 v40, 2, v40
	v_xor_b32_e32 v41, 4, v104
	v_cmp_lt_i32_e64 s[12:13], v41, v43
	s_waitcnt lgkmcnt(0)
	v_pk_add_f32 v[32:33], v[32:33], v[34:35]
	s_nop 1
	v_mov_b32_dpp v34, v32 row_ror:8 row_mask:0xf bank_mask:0xf
	v_mov_b32_dpp v35, v33 row_ror:8 row_mask:0xf bank_mask:0xf
	v_cndmask_b32_e64 v41, v104, v41, s[12:13]
	v_lshlrev_b32_e32 v41, 2, v41
	v_xor_b32_e32 v42, 2, v104
	v_cmp_lt_i32_e64 s[12:13], v42, v43
	v_pk_add_f32 v[32:33], v[32:33], v[34:35]
	s_nop 1
	v_mov_b32_dpp v34, v32 row_ror:4 row_mask:0xf bank_mask:0xf
	v_mov_b32_dpp v35, v33 row_ror:4 row_mask:0xf bank_mask:0xf
	v_cndmask_b32_e64 v42, v104, v42, s[12:13]
	v_lshlrev_b32_e32 v42, 2, v42
	v_xor_b32_e32 v47, 1, v104
	v_cmp_lt_i32_e64 s[12:13], v47, v43
	v_pk_add_f32 v[32:33], v[32:33], v[34:35]
	s_nop 1
	v_mov_b32_dpp v34, v32 quad_perm:[2,3,0,1] row_mask:0xf bank_mask:0xf
	v_mov_b32_dpp v35, v33 quad_perm:[2,3,0,1] row_mask:0xf bank_mask:0xf
	v_cndmask_b32_e64 v43, v104, v47, s[12:13]
	v_lshlrev_b32_e32 v43, 2, v43
	v_lshl_add_u32 v36, v48, 2, v37
	v_lshlrev_b32_e32 v47, 16, v110
	v_pk_add_f32 v[32:33], v[32:33], v[34:35]
	s_nop 1
	v_mov_b32_dpp v34, v32 quad_perm:[1,0,3,2] row_mask:0xf bank_mask:0xf
	v_mov_b32_dpp v35, v33 quad_perm:[1,0,3,2] row_mask:0xf bank_mask:0xf
	v_add_u32_e32 v59, v36, v92
	v_mul_f32_e64 v44, v44, -v46
	ds_write_b32 v59, v47 offset:1024
	ds_write2st64_b32 v59, v44, v158 offset1:1
	ds_write2st64_b32 v59, v159, v50 offset0:2 offset1:3
	s_and_saveexec_b64 s[12:13], s[4:5]
	s_cbranch_execz .LBB0_481
	s_waitcnt lgkmcnt(3)
	v_pk_add_f32 v[32:33], v[32:33], v[34:35]
	v_add_u32_e32 v34, v37, v93
	ds_write_b64 v34, v[32:33] offset:20736
.LBB0_481:
	s_or_b64 exec, exec, s[12:13]
	v_lshlrev_b32_e32 v32, 16, v121
	v_sub_f32_e32 v32, 1.0, v32
	v_mul_f32_e32 v46, v32, v45
	v_lshlrev_b32_e32 v33, 16, v107
	v_rcp_f32_e32 v32, v46
	s_waitcnt lgkmcnt(4)
	v_lshlrev_b32_e32 v34, 16, v120
	v_mul_f32_e32 v50, v46, v33
	v_add_f32_e32 v33, -1.0, v34
	v_lshlrev_b32_e32 v158, 16, v118
	s_waitcnt lgkmcnt(3)
	v_lshlrev_b32_e32 v35, 16, v109
	v_fma_f32 v159, v105, v33, 1.0
	v_pk_mul_f32 v[34:35], v[158:159], v[34:35]
	v_lshlrev_b32_e32 v47, 16, v116
	v_pk_mul_f32 v[162:163], v[34:35], v[32:33] op_sel_hi:[1,0]
	v_add_u32_e32 v44, v36, v94
	v_pk_mul_f32 v[32:33], v[50:51], v[162:163] op_sel_hi:[0,1]
	ds_bpermute_b32 v32, v38, v32
	ds_bpermute_b32 v33, v38, v33
	v_mul_f32_e64 v45, v45, -v158
	ds_write_b32 v44, v47 offset:1024
	ds_write2st64_b32 v44, v45, v162 offset1:1
	ds_write2st64_b32 v44, v163, v50 offset0:2 offset1:3
	s_waitcnt lgkmcnt(3)
	v_pk_fma_f32 v[32:33], v[50:51], v[162:163], v[32:33] op_sel_hi:[0,1,1]
	ds_bpermute_b32 v34, v39, v32
	ds_bpermute_b32 v35, v39, v33
	s_waitcnt lgkmcnt(0)
	v_pk_add_f32 v[32:33], v[32:33], v[34:35]
	s_nop 1
	v_mov_b32_dpp v34, v32 row_ror:8 row_mask:0xf bank_mask:0xf
	v_mov_b32_dpp v35, v33 row_ror:8 row_mask:0xf bank_mask:0xf
	v_pk_add_f32 v[32:33], v[32:33], v[34:35]
	s_nop 1
	v_mov_b32_dpp v34, v32 row_ror:4 row_mask:0xf bank_mask:0xf
	v_mov_b32_dpp v35, v33 row_ror:4 row_mask:0xf bank_mask:0xf
	v_pk_add_f32 v[32:33], v[32:33], v[34:35]
	s_nop 1
	v_mov_b32_dpp v34, v32 quad_perm:[2,3,0,1] row_mask:0xf bank_mask:0xf
	v_mov_b32_dpp v35, v33 quad_perm:[2,3,0,1] row_mask:0xf bank_mask:0xf
	v_pk_add_f32 v[32:33], v[32:33], v[34:35]
	s_nop 1
	v_mov_b32_dpp v34, v32 quad_perm:[1,0,3,2] row_mask:0xf bank_mask:0xf
	v_mov_b32_dpp v35, v33 quad_perm:[1,0,3,2] row_mask:0xf bank_mask:0xf
	s_and_saveexec_b64 s[12:13], s[4:5]
	s_cbranch_execz .LBB0_483
	s_waitcnt lgkmcnt(0)
	v_pk_add_f32 v[32:33], v[32:33], v[34:35]
	v_add_u32_e32 v34, v37, v95
	ds_write_b64 v34, v[32:33] offset:20736
.LBB0_483:
	s_or_b64 exec, exec, s[12:13]
	v_lshlrev_b32_e32 v32, 16, v129
	v_sub_f32_e32 v32, 1.0, v32
	v_mul_f32_e32 v45, v32, v46
	v_lshlrev_b32_e32 v33, 16, v114
	v_rcp_f32_e32 v32, v45
	s_waitcnt lgkmcnt(1)
	v_lshlrev_b32_e32 v34, 16, v126
	v_mul_f32_e32 v50, v45, v33
	v_add_f32_e32 v33, -1.0, v34
	v_lshlrev_b32_e32 v158, 16, v119
	s_waitcnt lgkmcnt(0)
	v_lshlrev_b32_e32 v35, 16, v115
	v_fma_f32 v159, v105, v33, 1.0
	v_pk_mul_f32 v[34:35], v[158:159], v[34:35]
	v_lshlrev_b32_e32 v47, 16, v117
	v_pk_mul_f32 v[162:163], v[34:35], v[32:33] op_sel_hi:[1,0]
	v_mul_f32_e64 v46, v46, -v158
	v_pk_mul_f32 v[32:33], v[50:51], v[162:163] op_sel_hi:[0,1]
	ds_bpermute_b32 v32, v38, v32
	ds_bpermute_b32 v33, v38, v33
	ds_write_b32 v44, v47 offset:2304
	ds_write2st64_b32 v44, v46, v162 offset0:5 offset1:6
	ds_write2st64_b32 v44, v163, v50 offset0:7 offset1:8
	s_waitcnt lgkmcnt(3)
	v_pk_fma_f32 v[32:33], v[50:51], v[162:163], v[32:33] op_sel_hi:[0,1,1]
	ds_bpermute_b32 v34, v39, v32
	ds_bpermute_b32 v35, v39, v33
	s_waitcnt lgkmcnt(0)
	v_pk_add_f32 v[32:33], v[32:33], v[34:35]
	s_nop 1
	v_mov_b32_dpp v34, v32 row_ror:8 row_mask:0xf bank_mask:0xf
	v_mov_b32_dpp v35, v33 row_ror:8 row_mask:0xf bank_mask:0xf
	v_pk_add_f32 v[32:33], v[32:33], v[34:35]
	s_nop 1
	v_mov_b32_dpp v34, v32 row_ror:4 row_mask:0xf bank_mask:0xf
	v_mov_b32_dpp v35, v33 row_ror:4 row_mask:0xf bank_mask:0xf
	v_pk_add_f32 v[32:33], v[32:33], v[34:35]
	s_nop 1
	v_mov_b32_dpp v34, v32 quad_perm:[2,3,0,1] row_mask:0xf bank_mask:0xf
	v_mov_b32_dpp v35, v33 quad_perm:[2,3,0,1] row_mask:0xf bank_mask:0xf
	v_pk_add_f32 v[32:33], v[32:33], v[34:35]
	s_nop 1
	v_mov_b32_dpp v34, v32 quad_perm:[1,0,3,2] row_mask:0xf bank_mask:0xf
	v_mov_b32_dpp v35, v33 quad_perm:[1,0,3,2] row_mask:0xf bank_mask:0xf
	s_and_saveexec_b64 s[12:13], s[4:5]
	s_cbranch_execz .LBB0_485
	s_waitcnt lgkmcnt(0)
	v_pk_add_f32 v[32:33], v[32:33], v[34:35]
	v_add_u32_e32 v34, v37, v96
	ds_write_b64 v34, v[32:33] offset:20736
.LBB0_485:
	s_or_b64 exec, exec, s[12:13]
	v_lshlrev_b32_e32 v32, 16, v128
	v_sub_f32_e32 v32, 1.0, v32
	v_mul_f32_e32 v46, v32, v45
	v_lshlrev_b32_e32 v33, 16, v122
	v_rcp_f32_e32 v32, v46
	s_waitcnt lgkmcnt(1)
	v_lshlrev_b32_e32 v34, 16, v127
	v_mul_f32_e32 v50, v46, v33
	v_add_f32_e32 v33, -1.0, v34
	v_lshlrev_b32_e32 v158, 16, v125
	s_waitcnt lgkmcnt(0)
	v_lshlrev_b32_e32 v35, 16, v123
	v_fma_f32 v159, v105, v33, 1.0
	v_pk_mul_f32 v[34:35], v[158:159], v[34:35]
	v_lshlrev_b32_e32 v47, 16, v124
	v_pk_mul_f32 v[162:163], v[34:35], v[32:33] op_sel_hi:[1,0]
	v_mul_f32_e64 v45, v45, -v158
	v_pk_mul_f32 v[32:33], v[50:51], v[162:163] op_sel_hi:[0,1]
	ds_bpermute_b32 v32, v38, v32
	ds_bpermute_b32 v33, v38, v33
	ds_write_b32 v44, v47 offset:3584
	ds_write2st64_b32 v44, v45, v162 offset0:10 offset1:11
	ds_write2st64_b32 v44, v163, v50 offset0:12 offset1:13
	s_waitcnt lgkmcnt(3)
	v_pk_fma_f32 v[32:33], v[50:51], v[162:163], v[32:33] op_sel_hi:[0,1,1]
	ds_bpermute_b32 v34, v39, v32
	ds_bpermute_b32 v35, v39, v33
	s_waitcnt lgkmcnt(0)
	v_pk_add_f32 v[32:33], v[32:33], v[34:35]
	s_nop 1
	v_mov_b32_dpp v34, v32 row_ror:8 row_mask:0xf bank_mask:0xf
	v_mov_b32_dpp v35, v33 row_ror:8 row_mask:0xf bank_mask:0xf
	v_pk_add_f32 v[32:33], v[32:33], v[34:35]
	s_nop 1
	v_mov_b32_dpp v34, v32 row_ror:4 row_mask:0xf bank_mask:0xf
	v_mov_b32_dpp v35, v33 row_ror:4 row_mask:0xf bank_mask:0xf
	v_pk_add_f32 v[32:33], v[32:33], v[34:35]
	s_nop 1
	v_mov_b32_dpp v34, v32 quad_perm:[2,3,0,1] row_mask:0xf bank_mask:0xf
	v_mov_b32_dpp v35, v33 quad_perm:[2,3,0,1] row_mask:0xf bank_mask:0xf
	v_pk_add_f32 v[32:33], v[32:33], v[34:35]
	s_nop 1
	v_mov_b32_dpp v34, v32 quad_perm:[1,0,3,2] row_mask:0xf bank_mask:0xf
	v_mov_b32_dpp v35, v33 quad_perm:[1,0,3,2] row_mask:0xf bank_mask:0xf
	s_and_saveexec_b64 s[12:13], s[4:5]
	s_cbranch_execz .LBB0_487
	s_waitcnt lgkmcnt(0)
	v_pk_add_f32 v[32:33], v[32:33], v[34:35]
	v_add_u32_e32 v34, v37, v97
	ds_write_b64 v34, v[32:33] offset:20736
.LBB0_487:
	s_or_b64 exec, exec, s[12:13]
	v_lshlrev_b32_e32 v32, 16, v137
	v_sub_f32_e32 v32, 1.0, v32
	v_mul_f32_e32 v45, v32, v46
	v_lshlrev_b32_e32 v33, 16, v130
	v_rcp_f32_e32 v32, v45
	s_waitcnt lgkmcnt(1)
	v_lshlrev_b32_e32 v34, 16, v136
	v_mul_f32_e32 v50, v45, v33
	v_add_f32_e32 v33, -1.0, v34
	v_lshlrev_b32_e32 v158, 16, v135
	s_waitcnt lgkmcnt(0)
	v_lshlrev_b32_e32 v35, 16, v132
	v_fma_f32 v159, v105, v33, 1.0
	v_pk_mul_f32 v[34:35], v[158:159], v[34:35]
	v_lshlrev_b32_e32 v47, 16, v134
	v_pk_mul_f32 v[162:163], v[34:35], v[32:33] op_sel_hi:[1,0]
	v_mul_f32_e64 v46, v46, -v158
	v_pk_mul_f32 v[32:33], v[50:51], v[162:163] op_sel_hi:[0,1]
	ds_bpermute_b32 v32, v38, v32
	ds_bpermute_b32 v33, v38, v33
	ds_write_b32 v44, v47 offset:4864
	ds_write2st64_b32 v44, v46, v162 offset0:15 offset1:16
	ds_write2st64_b32 v44, v163, v50 offset0:17 offset1:18
	s_waitcnt lgkmcnt(3)
	v_pk_fma_f32 v[32:33], v[50:51], v[162:163], v[32:33] op_sel_hi:[0,1,1]
	ds_bpermute_b32 v34, v39, v32
	ds_bpermute_b32 v35, v39, v33
	s_waitcnt lgkmcnt(0)
	v_pk_add_f32 v[32:33], v[32:33], v[34:35]
	s_nop 1
	v_mov_b32_dpp v34, v32 row_ror:8 row_mask:0xf bank_mask:0xf
	v_mov_b32_dpp v35, v33 row_ror:8 row_mask:0xf bank_mask:0xf
	v_pk_add_f32 v[32:33], v[32:33], v[34:35]
	s_nop 1
	v_mov_b32_dpp v34, v32 row_ror:4 row_mask:0xf bank_mask:0xf
	v_mov_b32_dpp v35, v33 row_ror:4 row_mask:0xf bank_mask:0xf
	v_pk_add_f32 v[32:33], v[32:33], v[34:35]
	s_nop 1
	v_mov_b32_dpp v34, v32 quad_perm:[2,3,0,1] row_mask:0xf bank_mask:0xf
	v_mov_b32_dpp v35, v33 quad_perm:[2,3,0,1] row_mask:0xf bank_mask:0xf
	v_pk_add_f32 v[32:33], v[32:33], v[34:35]
	s_nop 1
	v_mov_b32_dpp v34, v32 quad_perm:[1,0,3,2] row_mask:0xf bank_mask:0xf
	v_mov_b32_dpp v35, v33 quad_perm:[1,0,3,2] row_mask:0xf bank_mask:0xf
	s_and_saveexec_b64 s[12:13], s[4:5]
	s_cbranch_execz .LBB0_489
	s_waitcnt lgkmcnt(0)
	v_pk_add_f32 v[32:33], v[32:33], v[34:35]
	v_add_u32_e32 v34, v37, v98
	ds_write_b64 v34, v[32:33] offset:20736
.LBB0_489:
	s_or_b64 exec, exec, s[12:13]
	v_lshlrev_b32_e32 v32, 16, v145
	v_sub_f32_e32 v32, 1.0, v32
	v_mul_f32_e32 v46, v32, v45
	v_lshlrev_b32_e32 v33, 16, v131
	v_rcp_f32_e32 v32, v46
	s_waitcnt lgkmcnt(1)
	v_lshlrev_b32_e32 v34, 16, v144
	v_mul_f32_e32 v50, v46, v33
	v_add_f32_e32 v33, -1.0, v34
	v_lshlrev_b32_e32 v158, 16, v142
	s_waitcnt lgkmcnt(0)
	v_lshlrev_b32_e32 v35, 16, v133
	v_fma_f32 v159, v105, v33, 1.0
	v_pk_mul_f32 v[34:35], v[158:159], v[34:35]
	v_lshlrev_b32_e32 v47, 16, v140
	v_pk_mul_f32 v[162:163], v[34:35], v[32:33] op_sel_hi:[1,0]
	v_mul_f32_e64 v45, v45, -v158
	v_pk_mul_f32 v[32:33], v[50:51], v[162:163] op_sel_hi:[0,1]
	ds_bpermute_b32 v32, v38, v32
	ds_bpermute_b32 v33, v38, v33
	ds_write_b32 v44, v47 offset:6144
	ds_write2st64_b32 v44, v45, v162 offset0:20 offset1:21
	ds_write2st64_b32 v44, v163, v50 offset0:22 offset1:23
	s_waitcnt lgkmcnt(3)
	v_pk_fma_f32 v[32:33], v[50:51], v[162:163], v[32:33] op_sel_hi:[0,1,1]
	ds_bpermute_b32 v34, v39, v32
	ds_bpermute_b32 v35, v39, v33
	s_waitcnt lgkmcnt(0)
	v_pk_add_f32 v[32:33], v[32:33], v[34:35]
	s_nop 1
	v_mov_b32_dpp v34, v32 row_ror:8 row_mask:0xf bank_mask:0xf
	v_mov_b32_dpp v35, v33 row_ror:8 row_mask:0xf bank_mask:0xf
	v_pk_add_f32 v[32:33], v[32:33], v[34:35]
	s_nop 1
	v_mov_b32_dpp v34, v32 row_ror:4 row_mask:0xf bank_mask:0xf
	v_mov_b32_dpp v35, v33 row_ror:4 row_mask:0xf bank_mask:0xf
	v_pk_add_f32 v[32:33], v[32:33], v[34:35]
	s_nop 1
	v_mov_b32_dpp v34, v32 quad_perm:[2,3,0,1] row_mask:0xf bank_mask:0xf
	v_mov_b32_dpp v35, v33 quad_perm:[2,3,0,1] row_mask:0xf bank_mask:0xf
	v_pk_add_f32 v[32:33], v[32:33], v[34:35]
	s_nop 1
	v_mov_b32_dpp v34, v32 quad_perm:[1,0,3,2] row_mask:0xf bank_mask:0xf
	v_mov_b32_dpp v35, v33 quad_perm:[1,0,3,2] row_mask:0xf bank_mask:0xf
	s_and_saveexec_b64 s[12:13], s[4:5]
	s_cbranch_execz .LBB0_491
	s_waitcnt lgkmcnt(0)
	v_pk_add_f32 v[32:33], v[32:33], v[34:35]
	v_add_u32_e32 v34, v37, v99
	ds_write_b64 v34, v[32:33] offset:20736
.LBB0_491:
	s_or_b64 exec, exec, s[12:13]
	v_lshlrev_b32_e32 v32, 16, v153
	v_sub_f32_e32 v32, 1.0, v32
	v_mul_f32_e32 v45, v32, v46
	v_lshlrev_b32_e32 v33, 16, v138
	v_rcp_f32_e32 v32, v45
	s_waitcnt lgkmcnt(1)
	v_lshlrev_b32_e32 v34, 16, v150
	v_mul_f32_e32 v50, v45, v33
	v_add_f32_e32 v33, -1.0, v34
	v_lshlrev_b32_e32 v158, 16, v143
	s_waitcnt lgkmcnt(0)
	v_lshlrev_b32_e32 v35, 16, v139
	v_fma_f32 v159, v105, v33, 1.0
	v_pk_mul_f32 v[34:35], v[158:159], v[34:35]
	v_lshlrev_b32_e32 v47, 16, v141
	v_pk_mul_f32 v[162:163], v[34:35], v[32:33] op_sel_hi:[1,0]
	v_mul_f32_e64 v46, v46, -v158
	v_pk_mul_f32 v[32:33], v[50:51], v[162:163] op_sel_hi:[0,1]
	ds_bpermute_b32 v32, v38, v32
	ds_bpermute_b32 v33, v38, v33
	ds_write_b32 v44, v47 offset:7424
	ds_write2st64_b32 v44, v46, v162 offset0:25 offset1:26
	ds_write2st64_b32 v44, v163, v50 offset0:27 offset1:28
	s_waitcnt lgkmcnt(3)
	v_pk_fma_f32 v[32:33], v[50:51], v[162:163], v[32:33] op_sel_hi:[0,1,1]
	ds_bpermute_b32 v34, v39, v32
	ds_bpermute_b32 v35, v39, v33
	s_waitcnt lgkmcnt(0)
	v_pk_add_f32 v[32:33], v[32:33], v[34:35]
	s_nop 1
	v_mov_b32_dpp v34, v32 row_ror:8 row_mask:0xf bank_mask:0xf
	v_mov_b32_dpp v35, v33 row_ror:8 row_mask:0xf bank_mask:0xf
	v_pk_add_f32 v[32:33], v[32:33], v[34:35]
	s_nop 1
	v_mov_b32_dpp v34, v32 row_ror:4 row_mask:0xf bank_mask:0xf
	v_mov_b32_dpp v35, v33 row_ror:4 row_mask:0xf bank_mask:0xf
	v_pk_add_f32 v[32:33], v[32:33], v[34:35]
	s_nop 1
	v_mov_b32_dpp v34, v32 quad_perm:[2,3,0,1] row_mask:0xf bank_mask:0xf
	v_mov_b32_dpp v35, v33 quad_perm:[2,3,0,1] row_mask:0xf bank_mask:0xf
	v_pk_add_f32 v[32:33], v[32:33], v[34:35]
	s_nop 1
	v_mov_b32_dpp v34, v32 quad_perm:[1,0,3,2] row_mask:0xf bank_mask:0xf
	v_mov_b32_dpp v35, v33 quad_perm:[1,0,3,2] row_mask:0xf bank_mask:0xf
	s_and_saveexec_b64 s[12:13], s[4:5]
	s_cbranch_execz .LBB0_493
	s_waitcnt lgkmcnt(0)
	v_pk_add_f32 v[32:33], v[32:33], v[34:35]
	v_add_u32_e32 v34, v37, v100
	ds_write_b64 v34, v[32:33] offset:20736
.LBB0_493:
	s_or_b64 exec, exec, s[12:13]
	v_lshlrev_b32_e32 v32, 16, v152
	v_sub_f32_e32 v32, 1.0, v32
	v_mul_f32_e32 v46, v32, v45
	v_lshlrev_b32_e32 v33, 16, v146
	v_rcp_f32_e32 v32, v46
	s_waitcnt lgkmcnt(1)
	v_lshlrev_b32_e32 v34, 16, v151
	v_mul_f32_e32 v50, v46, v33
	v_add_f32_e32 v33, -1.0, v34
	v_lshlrev_b32_e32 v158, 16, v149
	s_waitcnt lgkmcnt(0)
	v_lshlrev_b32_e32 v35, 16, v147
	v_fma_f32 v159, v105, v33, 1.0
	v_pk_mul_f32 v[34:35], v[158:159], v[34:35]
	s_nop 0
	v_pk_mul_f32 v[162:163], v[34:35], v[32:33] op_sel_hi:[1,0]
	s_nop 0
	v_pk_mul_f32 v[32:33], v[50:51], v[162:163] op_sel_hi:[0,1]
	ds_bpermute_b32 v32, v38, v32
	ds_bpermute_b32 v33, v38, v33
	v_lshlrev_b32_e32 v38, 16, v148
	s_waitcnt lgkmcnt(0)
	v_pk_fma_f32 v[32:33], v[50:51], v[162:163], v[32:33] op_sel_hi:[0,1,1]
	ds_bpermute_b32 v34, v39, v32
	ds_bpermute_b32 v35, v39, v33
	v_mul_f32_e64 v39, v45, -v158
	ds_write_b32 v44, v38 offset:8704
	ds_write2st64_b32 v44, v39, v162 offset0:30 offset1:31
	ds_write2st64_b32 v44, v163, v50 offset0:32 offset1:33
	s_waitcnt lgkmcnt(3)
	v_pk_add_f32 v[32:33], v[32:33], v[34:35]
	s_nop 1
	v_mov_b32_dpp v34, v32 row_ror:8 row_mask:0xf bank_mask:0xf
	v_mov_b32_dpp v35, v33 row_ror:8 row_mask:0xf bank_mask:0xf
	s_waitcnt lgkmcnt(0)
	v_pk_add_f32 v[32:33], v[32:33], v[34:35]
	s_nop 1
	v_mov_b32_dpp v34, v32 row_ror:4 row_mask:0xf bank_mask:0xf
	v_mov_b32_dpp v35, v33 row_ror:4 row_mask:0xf bank_mask:0xf
	v_pk_add_f32 v[32:33], v[32:33], v[34:35]
	s_nop 1
	v_mov_b32_dpp v34, v32 quad_perm:[2,3,0,1] row_mask:0xf bank_mask:0xf
	v_mov_b32_dpp v35, v33 quad_perm:[2,3,0,1] row_mask:0xf bank_mask:0xf
	v_pk_add_f32 v[32:33], v[32:33], v[34:35]
	s_nop 1
	v_mov_b32_dpp v34, v32 quad_perm:[1,0,3,2] row_mask:0xf bank_mask:0xf
	v_mov_b32_dpp v35, v33 quad_perm:[1,0,3,2] row_mask:0xf bank_mask:0xf
	s_and_saveexec_b64 s[12:13], s[4:5]
	s_cbranch_execz .LBB0_496
	s_waitcnt lgkmcnt(0)
	v_pk_add_f32 v[32:33], v[32:33], v[34:35]
	v_add_u32_e32 v34, v37, v101
	ds_write_b64 v34, v[32:33] offset:20736
	s_or_b64 exec, exec, s[12:13]
	s_and_saveexec_b64 s[12:13], s[10:11]
	s_cbranch_execnz .LBB0_497

.LBB0_767:
	s_add_u32 s10, s8, 0xa000000
	s_addc_u32 s11, s9, 0
	s_add_u32 s16, s8, 0x8800000
	s_addc_u32 s17, s9, 0
	s_and_b32 s58, s5, 3
	s_add_i32 m0, s54, 0x18000
	v_lshl_add_u64 v[6:7], v[6:7], 0, s[40:41]
	s_lshl_b32 s5, s4, 13
	s_lshl_b32 s18, s58, 12
	s_waitcnt vmcnt(4)
	s_barrier
	global_load_lds_dwordx4 v[6:7], off
	v_lshl_add_u64 v[4:5], v[4:5], 0, s[40:41]
	s_add_i32 m0, s54, 0x1a000
	s_add_i32 s59, s54, 0x8000
	s_add_i32 s60, s54, 0xa000
	global_load_lds_dwordx4 v[4:5], off
	v_lshl_add_u64 v[2:3], v[2:3], 0, s[40:41]
	s_mov_b32 m0, s59
	s_add_u32 s6, s28, 0x40080
	global_load_lds_dwordx4 v[2:3], off
	v_lshl_add_u64 v[0:1], v[0:1], 0, s[40:41]
	s_mov_b32 m0, s60
	s_addc_u32 s7, s29, 0
	global_load_lds_dwordx4 v[0:1], off
	s_add_i32 m0, s54, 0x1c000
	v_lshl_add_u64 v[0:1], s[6:7], 0, v[208:209]
	global_load_lds_dwordx4 v[0:1], off
	v_lshl_add_u64 v[0:1], s[6:7], 0, v[128:129]
	s_add_i32 m0, s54, 0x1e000
	s_mov_b32 s61, 0
	global_load_lds_dwordx4 v[0:1], off
	v_bfe_u32 v1, v11, 4, 2
	v_and_b32_e32 v0, 15, v11
	v_lshlrev_b32_e32 v3, 4, v1
	s_waitcnt vmcnt(0)
	v_lshl_or_b32 v142, s4, 6, v0
	v_lshl_or_b32 v0, v0, 6, v3
	v_lshlrev_b32_e32 v3, 2, v11
	v_and_b32_e32 v3, 32, v3
	v_bitop3_b32 v4, v0, s5, v3 bitop3:0xde
	v_bitop3_b32 v143, v0, s18, v3 bitop3:0xde
	v_lshlrev_b32_e32 v0, 14, v13
	v_and_b32_e32 v0, 0xffff8000, v0
	v_lshlrev_b32_e32 v2, 3, v1
	v_cmp_eq_u32_e64 s[4:5], 0, v1
	v_lshl_add_u32 v0, v12, 11, v0
	v_and_b32_e32 v1, 1, v13
	v_lshl_or_b32 v0, v1, 6, v0
	v_lshl_add_u32 v134, v14, 1, v0
	v_lshlrev_b32_e32 v0, 14, v8
	v_and_b32_e32 v0, 0xffff8000, v0
	v_lshl_add_u32 v0, v9, 11, v0
	v_and_b32_e32 v1, 1, v8
	v_lshl_or_b32 v0, v1, 6, v0
	v_lshl_or_b32 v144, s58, 5, v2
	v_mov_b32_e32 v135, v209
	v_lshl_add_u32 v136, v10, 1, v0
	v_mov_b32_e32 v137, v209
	v_add_u32_e32 v145, 0, v4
	s_mov_b32 s36, s75
	s_mov_b32 s38, s73
	s_barrier
	s_branch .LBB0_769

.LBB0_812:
	s_load_dwordx2 s[6:7], s[0:1], 0x148
	s_mov_b32 s53, s37
	v_mbcnt_lo_u32_b32 v11, -1, 0
	v_mbcnt_hi_u32_b32 v11, -1, v11
	s_xor_b64 s[54:55], s[14:15], -1
	v_or_b32_e32 v0, s33, v11
	s_lshl_b64 s[8:9], s[52:53], 20
	s_and_b64 vcc, exec, s[12:13]
	v_readfirstlane_b32 s30, v0
	s_cbranch_vccnz .LBB0_828
	v_lshlrev_b32_e32 v1, 4, v0
	v_add_u32_e32 v2, 0x2000, v1
	v_ashrrev_i32_e32 v3, 31, v2
	v_lshrrev_b32_e32 v3, 22, v3
	v_add_u32_e32 v3, v2, v3
	v_ashrrev_i32_e32 v8, 10, v3
	v_mul_i32_i24_e32 v4, 0x400, v8
	v_sub_u32_e32 v2, v2, v4
	v_lshrrev_b32_e32 v4, 4, v2
	v_bitop3_b32 v2, v4, v2, 32 bitop3:0x6c
	v_ashrrev_i32_e32 v4, 31, v2
	v_lshrrev_b32_e32 v4, 26, v4
	v_add_u32_e32 v4, v2, v4
	v_ashrrev_i32_e32 v9, 6, v4
	v_and_b32_e32 v4, 0xc0, v4
	v_sub_u32_e32 v2, v2, v4
	v_ashrrev_i16_sdwa v2, v250, sext(v2) dst_sel:DWORD dst_unused:UNUSED_PAD src0_sel:DWORD src1_sel:BYTE_0
	v_lshlrev_b32_e32 v3, 5, v8
	v_bfe_i32 v10, v2, 0, 16
	v_lshlrev_b32_e32 v2, 3, v8
	v_and_b32_e32 v3, 32, v3
	v_and_b32_e32 v2, -16, v2
	v_add_u32_e32 v2, v9, v2
	v_and_b32_e32 v4, 3, v9
	v_add_lshl_u32 v3, v3, v10, 1
	v_and_or_b32 v4, v2, s86, v4
	v_lshrrev_b32_e32 v5, 2, v2
	v_lshlrev_b32_e32 v6, 1, v2
	s_waitcnt vmcnt(0)
	v_lshl_add_u32 v130, v2, 11, v3
	v_ashrrev_i32_e32 v2, 31, v0
	v_lshrrev_b32_e32 v2, 26, v2
	v_add_u32_e32 v2, v0, v2
	v_bfe_i32 v0, v0, 27, 1
	v_lshrrev_b32_e32 v0, 22, v0
	v_add_u32_e32 v0, v1, v0
	v_and_b32_e32 v0, 0xfffffc00, v0
	v_sub_u32_e32 v0, v1, v0
	v_lshrrev_b32_e32 v1, 4, v0
	v_bitop3_b32 v0, v1, v0, 32 bitop3:0x6c
	v_ashrrev_i32_e32 v1, 31, v0
	v_lshrrev_b32_e32 v1, 26, v1
	v_add_u32_e32 v1, v0, v1
	s_waitcnt lgkmcnt(0)
	s_add_u32 s31, s6, 0xa000000
	v_ashrrev_i32_e32 v13, 6, v1
	v_and_b32_e32 v1, 0xc0, v1
	s_addc_u32 s36, s7, 0
	s_lshl_b64 s[4:5], s[8:9], 1
	v_sub_u32_e32 v0, v0, v1
	s_add_u32 s4, s6, s4
	v_ashrrev_i32_e32 v12, 6, v2
	v_ashrrev_i16_sdwa v0, v250, sext(v0) dst_sel:DWORD dst_unused:UNUSED_PAD src0_sel:DWORD src1_sel:BYTE_0
	s_addc_u32 s5, s7, s5
	v_bfe_i32 v14, v0, 0, 16
	v_lshlrev_b32_e32 v0, 3, v12
	s_add_u32 s47, s4, 0x11e0000
	v_and_b32_e32 v5, 4, v5
	v_and_b32_e32 v6, 24, v6
	v_and_b32_e32 v0, -16, v0
	s_addc_u32 s56, s5, 0
	s_ashr_i32 s5, s30, 6
	v_or3_b32 v4, v4, v5, v6
	v_add_u32_e32 v0, v13, v0
	s_ashr_i32 s4, s30, 8
	s_lshl_b32 s57, s5, 10
	v_lshl_add_u32 v128, v4, 11, v3
	v_lshlrev_b32_e32 v2, 5, v12
	v_and_b32_e32 v1, 3, v13
	v_lshrrev_b32_e32 v3, 2, v0
	v_lshlrev_b32_e32 v4, 1, v0
	v_and_b32_e32 v2, 32, v2
	v_and_or_b32 v1, v0, s86, v1
	v_and_b32_e32 v3, 4, v3
	v_and_b32_e32 v4, 24, v4
	s_add_u32 s26, s47, s94
	v_or3_b32 v1, v1, v3, v4
	v_add_lshl_u32 v2, v2, v14, 1
	s_addc_u32 s27, s56, 0
	s_add_i32 s58, s57, 0
	v_lshl_add_u32 v208, v1, 11, v2
	s_add_i32 m0, s58, 0x10000
	v_lshl_add_u32 v132, v0, 11, v2
	global_load_lds_dwordx4 v208, s[26:27]
	s_add_i32 m0, s58, 0x12000
	s_add_u32 s24, s31, s81
	global_load_lds_dwordx4 v128, s[26:27]
	s_addc_u32 s25, s36, 0
	s_mov_b32 m0, s58
	s_add_i32 s59, s58, 0x2000
	global_load_lds_dwordx4 v132, s[24:25]
	s_mov_b32 m0, s59
	s_add_u32 s10, s26, 0x40000
	global_load_lds_dwordx4 v130, s[24:25]
	s_addc_u32 s11, s27, 0
	s_add_i32 m0, s58, 0x14000
	v_mov_b32_e32 v129, v209
	global_load_lds_dwordx4 v208, s[10:11]
	s_add_i32 m0, s58, 0x16000
	v_mov_b32_e32 v133, v209
	global_load_lds_dwordx4 v128, s[10:11]
	s_add_u32 s10, s24, 0x40000
	s_addc_u32 s11, s25, 0
	s_add_i32 s60, s58, 0x4000
	s_mov_b32 m0, s60
	s_add_i32 s61, s58, 0x6000
	global_load_lds_dwordx4 v132, s[10:11]
	s_mov_b32 m0, s61
	v_mov_b32_e32 v131, v209
	global_load_lds_dwordx4 v130, s[10:11]
	v_lshl_add_u64 v[6:7], s[26:27], 0, v[208:209]
	v_lshl_add_u64 v[4:5], s[26:27], 0, v[128:129]
	v_lshl_add_u64 v[2:3], s[24:25], 0, v[132:133]
	s_cmp_lg_u32 s4, 1
	v_lshl_add_u64 v[0:1], s[24:25], 0, v[130:131]
	s_cbranch_scc1 .LBB0_815
	s_barrier
.LBB0_815:
	s_add_u32 s10, s6, 0x12000000
	s_addc_u32 s11, s7, 0
	s_add_u32 s14, s6, 0x8800000
	s_addc_u32 s15, s7, 0
	s_lshl_b32 s5, s5, 5
	s_and_b32 s5, s5, 0x60
	s_add_i32 m0, s58, 0x18000
	v_lshl_add_u64 v[6:7], v[6:7], 0, s[40:41]
	s_lshl_b32 s18, s4, 13
	s_lshl_b32 s19, s5, 7
	s_waitcnt vmcnt(4)
	s_barrier
	global_load_lds_dwordx4 v[6:7], off
	v_lshl_add_u64 v[4:5], v[4:5], 0, s[40:41]
	s_add_i32 m0, s58, 0x1a000
	s_add_i32 s62, s58, 0x8000
	s_add_i32 s63, s58, 0xa000
	global_load_lds_dwordx4 v[4:5], off
	v_lshl_add_u64 v[2:3], v[2:3], 0, s[40:41]
	s_mov_b32 m0, s62
	s_add_u32 s16, s26, 0x40080
	global_load_lds_dwordx4 v[2:3], off
	v_lshl_add_u64 v[0:1], v[0:1], 0, s[40:41]
	s_mov_b32 m0, s63
	s_addc_u32 s17, s27, 0
	global_load_lds_dwordx4 v[0:1], off
	s_add_i32 m0, s58, 0x1c000
	v_lshl_add_u64 v[0:1], s[16:17], 0, v[208:209]
	global_load_lds_dwordx4 v[0:1], off
	v_lshl_add_u64 v[0:1], s[16:17], 0, v[128:129]
	s_add_i32 m0, s58, 0x1e000
	v_mov_b32_e32 v135, v209
	global_load_lds_dwordx4 v[0:1], off
	v_lshrrev_b32_e32 v1, 1, v11
	v_and_b32_e32 v1, 24, v1
	v_and_b32_e32 v0, 15, v11
	v_lshlrev_b32_e32 v2, 1, v1
	s_waitcnt vmcnt(0)
	v_lshl_or_b32 v142, s4, 6, v0
	v_lshl_or_b32 v0, v0, 6, v2
	v_lshlrev_b32_e32 v2, 2, v11
	v_and_b32_e32 v2, 32, v2
	v_bitop3_b32 v3, v0, s18, v2 bitop3:0xde
	v_bitop3_b32 v143, v0, s19, v2 bitop3:0xde
	v_lshlrev_b32_e32 v0, 14, v12
	v_and_b32_e32 v0, 0xffff8000, v0
	v_or_b32_e32 v144, s5, v1
	v_lshl_add_u32 v0, v13, 11, v0
	v_and_b32_e32 v1, 1, v12
	v_lshl_or_b32 v0, v1, 6, v0
	v_lshl_add_u32 v134, v14, 1, v0
	v_lshlrev_b32_e32 v0, 14, v8
	v_and_b32_e32 v0, 0xffff8000, v0
	v_lshl_add_u32 v0, v9, 11, v0
	v_and_b32_e32 v1, 1, v8
	v_lshl_or_b32 v0, v1, 6, v0
	v_lshl_add_u32 v136, v10, 1, v0
	v_mov_b32_e32 v137, v209
	s_mov_b32 s64, 0
	v_add_u32_e32 v145, 0, v3
	s_mov_b32 s34, s75
	s_mov_b32 s35, s73
	s_barrier
